# work-queue next-index prefetch enabled through the queue tail (P2 and P3)
# speedup vs baseline: 1.0197x; 1.0093x over previous
; __global__ void __launch_bounds__(NWAVES * 64, 2) hybrid_fwd(Args args) {
;     ...
;                 for (;;) {
;                     if (threadIdx.x == 0) *slot = __hip_atomic_fetch_add(qc, 1u, __ATOMIC_RELAXED, __HIP_MEMORY_SCOPE_AGENT);
;                     __syncthreads();
;                     const int L = __builtin_amdgcn_readfirstlane((int)*slot);
;                     __syncthreads();
;                     if (L >= CHB * 16 * 32 + CHB * 16) break;
.LBB0_410:
	s_or_b64 exec, exec, s[4:5]
	v_mov_b32_e32 v0, s86
	s_waitcnt lgkmcnt(0)
	s_barrier
	ds_read_b32 v0, v0
	s_mov_b64 s[4:5], -1
	s_waitcnt lgkmcnt(0)
	s_barrier
	v_readfirstlane_b32 s46, v0
	s_cmpk_gt_i32 s46, 0x41f
	s_cbranch_scc1 .LBB0_405
	s_mov_b32 s99, 0
	s_cmpk_lt_i32 s46, 0x420
	s_cbranch_scc0 .Lq2_nopf
	s_mov_b32 s99, 1
	s_and_saveexec_b64 s[42:43], s[10:11]
	s_cbranch_execz .Lq2_nopx
	v_mov_b32_e32 v252, v230
	global_atomic_add v252, v1, v252, s[38:39] sc0

; __global__ void __launch_bounds__(NWAVES * 64, 2) hybrid_fwd(Args args) {
;     ...
;                 for (;;) {
;                     if (threadIdx.x == 0) *slot = __hip_atomic_fetch_add(qc, 1u, __ATOMIC_RELAXED, __HIP_MEMORY_SCOPE_AGENT);
;                     __syncthreads();
;                     const int L = __builtin_amdgcn_readfirstlane((int)*slot);
;                     __syncthreads();
;                     if (L >= 2 * CHB * 16 * 32) break;
.LBB0_541:
	s_or_b64 exec, exec, s[6:7]
	v_mov_b32_e32 v0, s86
	s_waitcnt lgkmcnt(0)
	s_barrier
	ds_read_b32 v0, v0
	s_mov_b64 s[6:7], -1
	s_waitcnt lgkmcnt(0)
	s_barrier
	v_readfirstlane_b32 s2, v0
	s_cmpk_gt_i32 s2, 0x7ff
	s_cbranch_scc1 .LBB0_536
	s_mov_b32 s99, 0
	s_cmpk_lt_i32 s2, 0x800
	s_cbranch_scc0 .Lq3_nopf
	s_mov_b32 s99, 1
	s_and_saveexec_b64 s[8:9], s[10:11]
	s_cbranch_execz .Lq3_nopx
	v_mov_b32_e32 v252, v230
	global_atomic_add v252, v1, v252, s[38:39] offset:256 sc0
